# stack: SGPR-base LDS-DMA form + setprio/wait cleanup in main loops + tail drains removed
# speedup vs baseline: 1.0072x; 1.0072x over previous
.LBB0_260:
	s_add_u32 s6, s4, 0xfffc0080
	s_addc_u32 s7, s5, -1
	s_add_i32 s35, 0, 0x10000
	s_cmp_eq_u32 s34, 12
	s_cselect_b32 s11, s21, s7
	s_cselect_b32 s10, s26, s6
	v_add_u32_e32 v146, s35, v139
	s_cselect_b32 s7, s19, s29
	s_cselect_b32 s6, s27, s28
	s_add_i32 s92, 0, 0x14000
	ds_read_b128 v[148:151], v146
	ds_read_b128 v[152:155], v146 offset:1024
	ds_read_b128 v[156:159], v146 offset:2048
	ds_read_b128 v[160:163], v146 offset:3072
	v_add_u32_e32 v146, s92, v139
	ds_read_b128 v[170:173], v146
	ds_read_b128 v[174:177], v146 offset:1024
	ds_read_b128 v[178:181], v146 offset:2048
	ds_read_b128 v[182:185], v146 offset:3072
	s_add_i32 m0, s40, 0xc000
	ds_read_b128 v[186:189], v168
	ds_read_b128 v[190:193], v168 offset:1024
	ds_read_b128 v[194:197], v168 offset:2048
	ds_read_b128 v[198:201], v168 offset:3072
	ds_read_b128 v[202:205], v168 offset:4096
	ds_read_b128 v[222:225], v168 offset:5120
	ds_read_b128 v[236:239], v168 offset:6144
	ds_read_b128 v[240:243], v168 offset:7168
	global_load_lds_dwordx4 v142, s[4:5]
	s_add_i32 m0, s40, 0xe000
	s_nop 0
	global_load_lds_dwordx4 v144, s[4:5]
	s_waitcnt vmcnt(8)
	s_waitcnt lgkmcnt(0)
	s_barrier
	s_setprio 1
	v_mfma_f32_16x16x32_bf16 v[124:127], v[148:151], v[186:189], v[124:127]
	v_mfma_f32_16x16x32_bf16 v[120:123], v[156:159], v[186:189], v[120:123]
	v_mfma_f32_16x16x32_bf16 v[108:111], v[148:151], v[194:197], v[108:111]
	v_mfma_f32_16x16x32_bf16 v[104:107], v[156:159], v[194:197], v[104:107]
	v_mfma_f32_16x16x32_bf16 v[92:95], v[148:151], v[202:205], v[92:95]
	v_mfma_f32_16x16x32_bf16 v[88:91], v[156:159], v[202:205], v[88:91]
	v_mfma_f32_16x16x32_bf16 v[76:79], v[148:151], v[236:239], v[76:79]
	v_mfma_f32_16x16x32_bf16 v[72:75], v[156:159], v[236:239], v[72:75]
	v_mfma_f32_16x16x32_bf16 v[124:127], v[152:155], v[190:193], v[124:127]
	v_mfma_f32_16x16x32_bf16 v[120:123], v[160:163], v[190:193], v[120:123]
	v_mfma_f32_16x16x32_bf16 v[108:111], v[152:155], v[198:201], v[108:111]
	v_mfma_f32_16x16x32_bf16 v[104:107], v[160:163], v[198:201], v[104:107]
	v_mfma_f32_16x16x32_bf16 v[92:95], v[152:155], v[222:225], v[92:95]
	v_mfma_f32_16x16x32_bf16 v[88:91], v[160:163], v[222:225], v[88:91]
	v_mfma_f32_16x16x32_bf16 v[76:79], v[152:155], v[240:243], v[76:79]
	v_mfma_f32_16x16x32_bf16 v[72:75], v[160:163], v[240:243], v[72:75]
	v_mfma_f32_16x16x32_bf16 v[116:119], v[170:173], v[186:189], v[116:119]
	v_mfma_f32_16x16x32_bf16 v[112:115], v[178:181], v[186:189], v[112:115]
	v_mfma_f32_16x16x32_bf16 v[100:103], v[170:173], v[194:197], v[100:103]
	v_mfma_f32_16x16x32_bf16 v[96:99], v[178:181], v[194:197], v[96:99]
	v_mfma_f32_16x16x32_bf16 v[84:87], v[170:173], v[202:205], v[84:87]
	v_mfma_f32_16x16x32_bf16 v[80:83], v[178:181], v[202:205], v[80:83]
	v_mfma_f32_16x16x32_bf16 v[68:71], v[170:173], v[236:239], v[68:71]
	v_mfma_f32_16x16x32_bf16 v[64:67], v[178:181], v[236:239], v[64:67]
	v_mfma_f32_16x16x32_bf16 v[116:119], v[174:177], v[190:193], v[116:119]
	v_mfma_f32_16x16x32_bf16 v[112:115], v[182:185], v[190:193], v[112:115]
	v_mfma_f32_16x16x32_bf16 v[100:103], v[174:177], v[198:201], v[100:103]
	v_mfma_f32_16x16x32_bf16 v[96:99], v[182:185], v[198:201], v[96:99]
	v_mfma_f32_16x16x32_bf16 v[84:87], v[174:177], v[222:225], v[84:87]
	v_mfma_f32_16x16x32_bf16 v[80:83], v[182:185], v[222:225], v[80:83]
	v_mfma_f32_16x16x32_bf16 v[68:71], v[174:177], v[240:243], v[68:71]
	v_mfma_f32_16x16x32_bf16 v[64:67], v[182:185], v[240:243], v[64:67]
	s_setprio 0
	s_barrier
	s_add_i32 s35, s35, s37
	v_lshl_add_u64 v[206:207], s[6:7], 0, v[132:133]
	s_mov_b32 m0, s35
	ds_read_b128 v[186:189], v168 offset:16384
	ds_read_b128 v[190:193], v168 offset:17408
	ds_read_b128 v[194:197], v168 offset:18432
	ds_read_b128 v[198:201], v168 offset:19456
	ds_read_b128 v[202:205], v168 offset:20480
	ds_read_b128 v[222:225], v168 offset:21504
	ds_read_b128 v[236:239], v168 offset:22528
	ds_read_b128 v[240:243], v168 offset:23552
	global_load_lds_dwordx4 v[206:207], off
	s_add_i32 m0, s35, 0x2000
	s_add_u32 vcc_lo, s6, 0x40000
	v_lshl_add_u64 v[244:245], s[6:7], 0, v[128:129]
	s_addc_u32 vcc_hi, s7, 0
	s_add_i32 s35, s92, s37
	global_load_lds_dwordx4 v[244:245], off
	s_mov_b32 m0, s35
	v_lshl_add_u64 v[248:249], s[10:11], 0, v[130:131]
	global_load_lds_dwordx4 v132, vcc
	s_add_i32 m0, s35, 0x2000
	s_nop 0
	global_load_lds_dwordx4 v128, vcc
	v_lshl_add_u64 v[246:247], s[10:11], 0, v[134:135]
	s_mov_b32 m0, s40
	s_nop 0
	global_load_lds_dwordx4 v[246:247], off
	s_mov_b32 m0, s41
	s_nop 0
	global_load_lds_dwordx4 v[248:249], off
	s_waitcnt vmcnt(8)
	s_waitcnt lgkmcnt(0)
	s_barrier
	s_setprio 1
	v_mfma_f32_16x16x32_bf16 v[60:63], v[148:151], v[186:189], v[60:63]
	v_mfma_f32_16x16x32_bf16 v[56:59], v[156:159], v[186:189], v[56:59]
	v_mfma_f32_16x16x32_bf16 v[44:47], v[148:151], v[194:197], v[44:47]
	v_mfma_f32_16x16x32_bf16 v[40:43], v[156:159], v[194:197], v[40:43]
	v_mfma_f32_16x16x32_bf16 v[28:31], v[148:151], v[202:205], v[28:31]
	v_mfma_f32_16x16x32_bf16 v[24:27], v[156:159], v[202:205], v[24:27]
	v_mfma_f32_16x16x32_bf16 v[12:15], v[148:151], v[236:239], v[12:15]
	v_mfma_f32_16x16x32_bf16 v[8:11], v[156:159], v[236:239], v[8:11]
	v_mfma_f32_16x16x32_bf16 v[60:63], v[152:155], v[190:193], v[60:63]
	v_mfma_f32_16x16x32_bf16 v[56:59], v[160:163], v[190:193], v[56:59]
	v_mfma_f32_16x16x32_bf16 v[44:47], v[152:155], v[198:201], v[44:47]
	v_mfma_f32_16x16x32_bf16 v[40:43], v[160:163], v[198:201], v[40:43]
	v_mfma_f32_16x16x32_bf16 v[28:31], v[152:155], v[222:225], v[28:31]
	v_mfma_f32_16x16x32_bf16 v[24:27], v[160:163], v[222:225], v[24:27]
	v_mfma_f32_16x16x32_bf16 v[12:15], v[152:155], v[240:243], v[12:15]
	v_mfma_f32_16x16x32_bf16 v[8:11], v[160:163], v[240:243], v[8:11]
	v_mfma_f32_16x16x32_bf16 v[52:55], v[170:173], v[186:189], v[52:55]
	v_mfma_f32_16x16x32_bf16 v[48:51], v[178:181], v[186:189], v[48:51]
	v_mfma_f32_16x16x32_bf16 v[36:39], v[170:173], v[194:197], v[36:39]
	v_mfma_f32_16x16x32_bf16 v[32:35], v[178:181], v[194:197], v[32:35]
	v_mfma_f32_16x16x32_bf16 v[20:23], v[170:173], v[202:205], v[20:23]
	v_mfma_f32_16x16x32_bf16 v[16:19], v[178:181], v[202:205], v[16:19]
	v_mfma_f32_16x16x32_bf16 v[4:7], v[170:173], v[236:239], v[4:7]
	v_mfma_f32_16x16x32_bf16 v[0:3], v[178:181], v[236:239], v[0:3]
	v_mfma_f32_16x16x32_bf16 v[52:55], v[174:177], v[190:193], v[52:55]
	v_mfma_f32_16x16x32_bf16 v[48:51], v[182:185], v[190:193], v[48:51]
	v_mfma_f32_16x16x32_bf16 v[36:39], v[174:177], v[198:201], v[36:39]
	v_mfma_f32_16x16x32_bf16 v[32:35], v[182:185], v[198:201], v[32:35]
	v_mfma_f32_16x16x32_bf16 v[20:23], v[174:177], v[222:225], v[20:23]
	v_mfma_f32_16x16x32_bf16 v[16:19], v[182:185], v[222:225], v[16:19]
	v_mfma_f32_16x16x32_bf16 v[4:7], v[174:177], v[240:243], v[4:7]
	v_mfma_f32_16x16x32_bf16 v[0:3], v[182:185], v[240:243], v[0:3]
	s_setprio 0
	s_barrier
	s_add_i32 s35, 0, 0x18000
	v_add_u32_e32 v146, s35, v139
	s_add_i32 s92, 0, 0x1c000
	ds_read_b128 v[148:151], v146
	ds_read_b128 v[152:155], v146 offset:1024
	ds_read_b128 v[156:159], v146 offset:2048
	ds_read_b128 v[160:163], v146 offset:3072
	v_add_u32_e32 v146, s92, v139
	ds_read_b128 v[170:173], v146
	ds_read_b128 v[174:177], v146 offset:1024
	ds_read_b128 v[178:181], v146 offset:2048
	ds_read_b128 v[182:185], v146 offset:3072
	s_add_u32 s10, s10, 0x40000
	s_addc_u32 s11, s11, 0
	s_mov_b32 m0, s42
	ds_read_b128 v[186:189], v168 offset:32768
	ds_read_b128 v[190:193], v168 offset:33792
	ds_read_b128 v[194:197], v168 offset:34816
	ds_read_b128 v[198:201], v168 offset:35840
	ds_read_b128 v[202:205], v168 offset:36864
	ds_read_b128 v[222:225], v168 offset:37888
	ds_read_b128 v[236:239], v168 offset:38912
	ds_read_b128 v[240:243], v168 offset:39936
	global_load_lds_dwordx4 v134, s[10:11]
	s_mov_b32 m0, s43
	s_nop 0
	global_load_lds_dwordx4 v130, s[10:11]
	s_waitcnt vmcnt(8)
	s_waitcnt lgkmcnt(0)
	s_barrier
	s_setprio 1
	v_mfma_f32_16x16x32_bf16 v[124:127], v[148:151], v[186:189], v[124:127]
	v_mfma_f32_16x16x32_bf16 v[120:123], v[156:159], v[186:189], v[120:123]
	v_mfma_f32_16x16x32_bf16 v[108:111], v[148:151], v[194:197], v[108:111]
	v_mfma_f32_16x16x32_bf16 v[104:107], v[156:159], v[194:197], v[104:107]
	v_mfma_f32_16x16x32_bf16 v[92:95], v[148:151], v[202:205], v[92:95]
	v_mfma_f32_16x16x32_bf16 v[88:91], v[156:159], v[202:205], v[88:91]
	v_mfma_f32_16x16x32_bf16 v[76:79], v[148:151], v[236:239], v[76:79]
	v_mfma_f32_16x16x32_bf16 v[72:75], v[156:159], v[236:239], v[72:75]
	v_mfma_f32_16x16x32_bf16 v[124:127], v[152:155], v[190:193], v[124:127]
	v_mfma_f32_16x16x32_bf16 v[120:123], v[160:163], v[190:193], v[120:123]
	v_mfma_f32_16x16x32_bf16 v[108:111], v[152:155], v[198:201], v[108:111]
	v_mfma_f32_16x16x32_bf16 v[104:107], v[160:163], v[198:201], v[104:107]
	v_mfma_f32_16x16x32_bf16 v[92:95], v[152:155], v[222:225], v[92:95]
	v_mfma_f32_16x16x32_bf16 v[88:91], v[160:163], v[222:225], v[88:91]
	v_mfma_f32_16x16x32_bf16 v[76:79], v[152:155], v[240:243], v[76:79]
	v_mfma_f32_16x16x32_bf16 v[72:75], v[160:163], v[240:243], v[72:75]
	v_mfma_f32_16x16x32_bf16 v[116:119], v[170:173], v[186:189], v[116:119]
	v_mfma_f32_16x16x32_bf16 v[112:115], v[178:181], v[186:189], v[112:115]
	v_mfma_f32_16x16x32_bf16 v[100:103], v[170:173], v[194:197], v[100:103]
	v_mfma_f32_16x16x32_bf16 v[96:99], v[178:181], v[194:197], v[96:99]
	v_mfma_f32_16x16x32_bf16 v[84:87], v[170:173], v[202:205], v[84:87]
	v_mfma_f32_16x16x32_bf16 v[80:83], v[178:181], v[202:205], v[80:83]
	v_mfma_f32_16x16x32_bf16 v[68:71], v[170:173], v[236:239], v[68:71]
	v_mfma_f32_16x16x32_bf16 v[64:67], v[178:181], v[236:239], v[64:67]
	v_mfma_f32_16x16x32_bf16 v[116:119], v[174:177], v[190:193], v[116:119]
	v_mfma_f32_16x16x32_bf16 v[112:115], v[182:185], v[190:193], v[112:115]
	v_mfma_f32_16x16x32_bf16 v[100:103], v[174:177], v[198:201], v[100:103]
	v_mfma_f32_16x16x32_bf16 v[96:99], v[182:185], v[198:201], v[96:99]
	v_mfma_f32_16x16x32_bf16 v[84:87], v[174:177], v[222:225], v[84:87]
	v_mfma_f32_16x16x32_bf16 v[80:83], v[182:185], v[222:225], v[80:83]
	v_mfma_f32_16x16x32_bf16 v[68:71], v[174:177], v[240:243], v[68:71]
	v_mfma_f32_16x16x32_bf16 v[64:67], v[182:185], v[240:243], v[64:67]
	s_setprio 0
	s_barrier
	s_add_i32 s10, s35, s37
	v_lshl_add_u64 v[206:207], v[206:207], 0, s[94:95]
	s_mov_b32 m0, s10
	ds_read_b128 v[186:189], v168 offset:49152
	ds_read_b128 v[190:193], v168 offset:50176
	ds_read_b128 v[194:197], v168 offset:51200
	ds_read_b128 v[198:201], v168 offset:52224
	ds_read_b128 v[202:205], v168 offset:53248
	ds_read_b128 v[222:225], v168 offset:54272
	ds_read_b128 v[236:239], v168 offset:55296
	ds_read_b128 v[240:243], v168 offset:56320
	global_load_lds_dwordx4 v[206:207], off
	s_add_i32 m0, s10, 0x2000
	s_add_u32 s6, s6, 0x40080
	v_lshl_add_u64 v[206:207], v[244:245], 0, s[94:95]
	s_addc_u32 s7, s7, 0
	s_add_i32 s10, s92, s37
	global_load_lds_dwordx4 v[206:207], off
	s_mov_b32 m0, s10
	s_nop 0
	global_load_lds_dwordx4 v132, s[6:7]
	v_lshl_add_u64 v[206:207], s[6:7], 0, v[128:129]
	s_add_i32 m0, s10, 0x2000
	s_nop 0
	global_load_lds_dwordx4 v[206:207], off
	v_lshl_add_u64 v[206:207], v[246:247], 0, s[94:95]
	s_mov_b32 m0, s76
	s_nop 0
	global_load_lds_dwordx4 v[206:207], off
	v_lshl_add_u64 v[206:207], v[248:249], 0, s[94:95]
	s_mov_b32 m0, s77
	s_nop 0
	global_load_lds_dwordx4 v[206:207], off
	s_waitcnt vmcnt(8)
	s_waitcnt lgkmcnt(0)
	s_barrier
	s_setprio 1
	v_mfma_f32_16x16x32_bf16 v[60:63], v[148:151], v[186:189], v[60:63]
	v_mfma_f32_16x16x32_bf16 v[56:59], v[156:159], v[186:189], v[56:59]
	v_mfma_f32_16x16x32_bf16 v[44:47], v[148:151], v[194:197], v[44:47]
	v_mfma_f32_16x16x32_bf16 v[40:43], v[156:159], v[194:197], v[40:43]
	v_mfma_f32_16x16x32_bf16 v[28:31], v[148:151], v[202:205], v[28:31]
	v_mfma_f32_16x16x32_bf16 v[24:27], v[156:159], v[202:205], v[24:27]
	v_mfma_f32_16x16x32_bf16 v[12:15], v[148:151], v[236:239], v[12:15]
	v_mfma_f32_16x16x32_bf16 v[8:11], v[156:159], v[236:239], v[8:11]
	v_mfma_f32_16x16x32_bf16 v[60:63], v[152:155], v[190:193], v[60:63]
	v_mfma_f32_16x16x32_bf16 v[56:59], v[160:163], v[190:193], v[56:59]
	v_mfma_f32_16x16x32_bf16 v[44:47], v[152:155], v[198:201], v[44:47]
	v_mfma_f32_16x16x32_bf16 v[40:43], v[160:163], v[198:201], v[40:43]
	v_mfma_f32_16x16x32_bf16 v[28:31], v[152:155], v[222:225], v[28:31]
	v_mfma_f32_16x16x32_bf16 v[24:27], v[160:163], v[222:225], v[24:27]
	v_mfma_f32_16x16x32_bf16 v[12:15], v[152:155], v[240:243], v[12:15]
	v_mfma_f32_16x16x32_bf16 v[8:11], v[160:163], v[240:243], v[8:11]
	v_mfma_f32_16x16x32_bf16 v[52:55], v[170:173], v[186:189], v[52:55]
	v_mfma_f32_16x16x32_bf16 v[48:51], v[178:181], v[186:189], v[48:51]
	v_mfma_f32_16x16x32_bf16 v[36:39], v[170:173], v[194:197], v[36:39]
	v_mfma_f32_16x16x32_bf16 v[32:35], v[178:181], v[194:197], v[32:35]
	v_mfma_f32_16x16x32_bf16 v[20:23], v[170:173], v[202:205], v[20:23]
	v_mfma_f32_16x16x32_bf16 v[16:19], v[178:181], v[202:205], v[16:19]
	v_mfma_f32_16x16x32_bf16 v[4:7], v[170:173], v[236:239], v[4:7]
	v_mfma_f32_16x16x32_bf16 v[0:3], v[178:181], v[236:239], v[0:3]
	v_mfma_f32_16x16x32_bf16 v[52:55], v[174:177], v[190:193], v[52:55]
	v_mfma_f32_16x16x32_bf16 v[48:51], v[182:185], v[190:193], v[48:51]
	v_mfma_f32_16x16x32_bf16 v[36:39], v[174:177], v[198:201], v[36:39]
	v_mfma_f32_16x16x32_bf16 v[32:35], v[182:185], v[198:201], v[32:35]
	v_mfma_f32_16x16x32_bf16 v[20:23], v[174:177], v[222:225], v[20:23]
	v_mfma_f32_16x16x32_bf16 v[16:19], v[182:185], v[222:225], v[16:19]
	v_mfma_f32_16x16x32_bf16 v[4:7], v[174:177], v[240:243], v[4:7]
	v_mfma_f32_16x16x32_bf16 v[0:3], v[182:185], v[240:243], v[0:3]
	s_setprio 0
	s_barrier
	s_add_i32 s34, s34, 2
	s_add_u32 s4, s4, 0x100
	s_addc_u32 s5, s5, 0
	s_add_u32 s28, s28, 0x100
	s_addc_u32 s29, s29, 0
	s_cmp_gt_u32 s34, 13
	s_cbranch_scc0 .LBB0_260
	v_and_b32_e32 v148, 15, v226
	v_bfe_u32 v149, v226, 4, 2
	v_bfe_u32 v150, v226, 6, 2
	v_lshrrev_b32_e32 v151, 8, v226
	v_lshl_add_u32 v152, v151, 6, v148
	v_lshlrev_b32_e32 v153, 2, v152
	s_lshl_b32 s4, s31, 10
	s_add_u32 s100, s96, s4
	s_addc_u32 s101, s97, 0
	global_load_dword v154, v153, s[100:101]
	global_load_dword v155, v153, s[100:101] offset:64
	global_load_dword v156, v153, s[100:101] offset:128
	global_load_dword v157, v153, s[100:101] offset:192
	global_load_dword v158, v153, s[100:101] offset:512
	global_load_dword v159, v153, s[100:101] offset:576
	global_load_dword v160, v153, s[100:101] offset:640
	global_load_dword v161, v153, s[100:101] offset:704
	s_and_b64 vcc, exec, s[16:17]
	s_cbranch_vccz .LBB0_263
	s_barrier

.LBB0_710:
	s_add_u32 s24, s22, 0xfffc0080
	s_addc_u32 s25, s23, -1
	s_add_i32 vcc_lo, 0, 0x10000
	s_cmp_eq_u32 s92, 12
	s_cselect_b32 s27, s17, s25
	s_cselect_b32 s26, s70, s24
	v_add_u32_e32 v142, vcc_lo, v145
	s_cselect_b32 s25, s15, s83
	s_cselect_b32 s24, s80, s82
	s_add_i32 s10, 0, 0x14000
	ds_read_b128 v[138:141], v142
	ds_read_b128 v[148:151], v142 offset:1024
	ds_read_b128 v[152:155], v142 offset:2048
	ds_read_b128 v[156:159], v142 offset:3072
	v_add_u32_e32 v142, s10, v145
	ds_read_b128 v[160:163], v142
	ds_read_b128 v[164:167], v142 offset:1024
	ds_read_b128 v[168:171], v142 offset:2048
	ds_read_b128 v[172:175], v142 offset:3072
	s_add_i32 m0, s31, 0xc000
	ds_read_b128 v[176:179], v147
	ds_read_b128 v[180:183], v147 offset:1024
	ds_read_b128 v[184:187], v147 offset:2048
	ds_read_b128 v[188:191], v147 offset:3072
	ds_read_b128 v[192:195], v147 offset:4096
	ds_read_b128 v[196:199], v147 offset:5120
	ds_read_b128 v[200:203], v147 offset:6144
	ds_read_b128 v[204:207], v147 offset:7168
	global_load_lds_dwordx4 v134, s[22:23]
	s_add_i32 m0, s31, 0xe000
	s_nop 0
	global_load_lds_dwordx4 v136, s[22:23]
	s_waitcnt vmcnt(8)
	s_waitcnt lgkmcnt(0)
	s_barrier
	s_setprio 1
	v_mfma_f32_16x16x32_bf16 v[124:127], v[138:141], v[176:179], v[124:127]
	v_mfma_f32_16x16x32_bf16 v[120:123], v[152:155], v[176:179], v[120:123]
	v_mfma_f32_16x16x32_bf16 v[108:111], v[138:141], v[184:187], v[108:111]
	v_mfma_f32_16x16x32_bf16 v[104:107], v[152:155], v[184:187], v[104:107]
	v_mfma_f32_16x16x32_bf16 v[92:95], v[138:141], v[192:195], v[92:95]
	v_mfma_f32_16x16x32_bf16 v[88:91], v[152:155], v[192:195], v[88:91]
	v_mfma_f32_16x16x32_bf16 v[76:79], v[138:141], v[200:203], v[76:79]
	v_mfma_f32_16x16x32_bf16 v[72:75], v[152:155], v[200:203], v[72:75]
	v_mfma_f32_16x16x32_bf16 v[124:127], v[148:151], v[180:183], v[124:127]
	v_mfma_f32_16x16x32_bf16 v[120:123], v[156:159], v[180:183], v[120:123]
	v_mfma_f32_16x16x32_bf16 v[108:111], v[148:151], v[188:191], v[108:111]
	v_mfma_f32_16x16x32_bf16 v[104:107], v[156:159], v[188:191], v[104:107]
	v_mfma_f32_16x16x32_bf16 v[92:95], v[148:151], v[196:199], v[92:95]
	v_mfma_f32_16x16x32_bf16 v[88:91], v[156:159], v[196:199], v[88:91]
	v_mfma_f32_16x16x32_bf16 v[76:79], v[148:151], v[204:207], v[76:79]
	v_mfma_f32_16x16x32_bf16 v[72:75], v[156:159], v[204:207], v[72:75]
	v_mfma_f32_16x16x32_bf16 v[116:119], v[160:163], v[176:179], v[116:119]
	v_mfma_f32_16x16x32_bf16 v[112:115], v[168:171], v[176:179], v[112:115]
	v_mfma_f32_16x16x32_bf16 v[100:103], v[160:163], v[184:187], v[100:103]
	v_mfma_f32_16x16x32_bf16 v[96:99], v[168:171], v[184:187], v[96:99]
	v_mfma_f32_16x16x32_bf16 v[84:87], v[160:163], v[192:195], v[84:87]
	v_mfma_f32_16x16x32_bf16 v[80:83], v[168:171], v[192:195], v[80:83]
	v_mfma_f32_16x16x32_bf16 v[68:71], v[160:163], v[200:203], v[68:71]
	v_mfma_f32_16x16x32_bf16 v[64:67], v[168:171], v[200:203], v[64:67]
	v_mfma_f32_16x16x32_bf16 v[116:119], v[164:167], v[180:183], v[116:119]
	v_mfma_f32_16x16x32_bf16 v[112:115], v[172:175], v[180:183], v[112:115]
	v_mfma_f32_16x16x32_bf16 v[100:103], v[164:167], v[188:191], v[100:103]
	v_mfma_f32_16x16x32_bf16 v[96:99], v[172:175], v[188:191], v[96:99]
	v_mfma_f32_16x16x32_bf16 v[84:87], v[164:167], v[196:199], v[84:87]
	v_mfma_f32_16x16x32_bf16 v[80:83], v[172:175], v[196:199], v[80:83]
	v_mfma_f32_16x16x32_bf16 v[68:71], v[164:167], v[204:207], v[68:71]
	v_mfma_f32_16x16x32_bf16 v[64:67], v[172:175], v[204:207], v[64:67]
	s_setprio 0
	s_barrier
	s_add_i32 s11, vcc_lo, s30
	v_lshl_add_u64 v[142:143], s[24:25], 0, v[208:209]
	s_mov_b32 m0, s11
	ds_read_b128 v[176:179], v147 offset:16384
	ds_read_b128 v[180:183], v147 offset:17408
	ds_read_b128 v[184:187], v147 offset:18432
	ds_read_b128 v[188:191], v147 offset:19456
	ds_read_b128 v[192:195], v147 offset:20480
	ds_read_b128 v[196:199], v147 offset:21504
	ds_read_b128 v[200:203], v147 offset:22528
	ds_read_b128 v[204:207], v147 offset:23552
	global_load_lds_dwordx4 v[142:143], off
	s_add_i32 m0, s11, 0x2000
	s_add_u32 vcc_lo, s24, 0x40000
	v_lshl_add_u64 v[222:223], s[24:25], 0, v[128:129]
	s_addc_u32 vcc_hi, s25, 0
	s_add_i32 s10, s10, s30
	global_load_lds_dwordx4 v[222:223], off
	s_mov_b32 m0, s10
	v_lshl_add_u64 v[236:237], s[26:27], 0, v[130:131]
	global_load_lds_dwordx4 v208, vcc
	s_add_i32 m0, s10, 0x2000
	s_nop 0
	global_load_lds_dwordx4 v128, vcc
	v_lshl_add_u64 v[224:225], s[26:27], 0, v[132:133]
	s_mov_b32 m0, s31
	s_nop 0
	global_load_lds_dwordx4 v[224:225], off
	s_mov_b32 m0, s34
	s_nop 0
	global_load_lds_dwordx4 v[236:237], off
	s_waitcnt vmcnt(8)
	s_waitcnt lgkmcnt(0)
	s_barrier
	s_setprio 1
	v_mfma_f32_16x16x32_bf16 v[60:63], v[138:141], v[176:179], v[60:63]
	v_mfma_f32_16x16x32_bf16 v[56:59], v[152:155], v[176:179], v[56:59]
	v_mfma_f32_16x16x32_bf16 v[44:47], v[138:141], v[184:187], v[44:47]
	v_mfma_f32_16x16x32_bf16 v[40:43], v[152:155], v[184:187], v[40:43]
	v_mfma_f32_16x16x32_bf16 v[28:31], v[138:141], v[192:195], v[28:31]
	v_mfma_f32_16x16x32_bf16 v[24:27], v[152:155], v[192:195], v[24:27]
	v_mfma_f32_16x16x32_bf16 v[12:15], v[138:141], v[200:203], v[12:15]
	v_mfma_f32_16x16x32_bf16 v[8:11], v[152:155], v[200:203], v[8:11]
	v_mfma_f32_16x16x32_bf16 v[60:63], v[148:151], v[180:183], v[60:63]
	v_mfma_f32_16x16x32_bf16 v[56:59], v[156:159], v[180:183], v[56:59]
	v_mfma_f32_16x16x32_bf16 v[44:47], v[148:151], v[188:191], v[44:47]
	v_mfma_f32_16x16x32_bf16 v[40:43], v[156:159], v[188:191], v[40:43]
	v_mfma_f32_16x16x32_bf16 v[28:31], v[148:151], v[196:199], v[28:31]
	v_mfma_f32_16x16x32_bf16 v[24:27], v[156:159], v[196:199], v[24:27]
	v_mfma_f32_16x16x32_bf16 v[12:15], v[148:151], v[204:207], v[12:15]
	v_mfma_f32_16x16x32_bf16 v[8:11], v[156:159], v[204:207], v[8:11]
	v_mfma_f32_16x16x32_bf16 v[52:55], v[160:163], v[176:179], v[52:55]
	v_mfma_f32_16x16x32_bf16 v[48:51], v[168:171], v[176:179], v[48:51]
	v_mfma_f32_16x16x32_bf16 v[36:39], v[160:163], v[184:187], v[36:39]
	v_mfma_f32_16x16x32_bf16 v[32:35], v[168:171], v[184:187], v[32:35]
	v_mfma_f32_16x16x32_bf16 v[20:23], v[160:163], v[192:195], v[20:23]
	v_mfma_f32_16x16x32_bf16 v[16:19], v[168:171], v[192:195], v[16:19]
	v_mfma_f32_16x16x32_bf16 v[4:7], v[160:163], v[200:203], v[4:7]
	v_mfma_f32_16x16x32_bf16 v[0:3], v[168:171], v[200:203], v[0:3]
	v_mfma_f32_16x16x32_bf16 v[52:55], v[164:167], v[180:183], v[52:55]
	v_mfma_f32_16x16x32_bf16 v[48:51], v[172:175], v[180:183], v[48:51]
	v_mfma_f32_16x16x32_bf16 v[36:39], v[164:167], v[188:191], v[36:39]
	v_mfma_f32_16x16x32_bf16 v[32:35], v[172:175], v[188:191], v[32:35]
	v_mfma_f32_16x16x32_bf16 v[20:23], v[164:167], v[196:199], v[20:23]
	v_mfma_f32_16x16x32_bf16 v[16:19], v[172:175], v[196:199], v[16:19]
	v_mfma_f32_16x16x32_bf16 v[4:7], v[164:167], v[204:207], v[4:7]
	v_mfma_f32_16x16x32_bf16 v[0:3], v[172:175], v[204:207], v[0:3]
	s_setprio 0
	s_barrier
	s_add_i32 s10, 0, 0x18000
	s_add_i32 s11, 0, 0x1c000
	v_add_u32_e32 v156, s10, v145
	v_add_u32_e32 v172, s11, v145
	ds_read_b128 v[138:141], v156
	ds_read_b128 v[148:151], v156 offset:1024
	ds_read_b128 v[152:155], v156 offset:2048
	ds_read_b128 v[156:159], v156 offset:3072
	ds_read_b128 v[160:163], v172
	ds_read_b128 v[164:167], v172 offset:1024
	ds_read_b128 v[168:171], v172 offset:2048
	ds_read_b128 v[172:175], v172 offset:3072
	s_add_u32 s26, s26, 0x40000
	s_addc_u32 s27, s27, 0
	s_mov_b32 m0, s35
	ds_read_b128 v[176:179], v147 offset:32768
	ds_read_b128 v[180:183], v147 offset:33792
	ds_read_b128 v[184:187], v147 offset:34816
	ds_read_b128 v[188:191], v147 offset:35840
	ds_read_b128 v[192:195], v147 offset:36864
	ds_read_b128 v[196:199], v147 offset:37888
	ds_read_b128 v[200:203], v147 offset:38912
	ds_read_b128 v[204:207], v147 offset:39936
	global_load_lds_dwordx4 v132, s[26:27]
	s_mov_b32 m0, s36
	s_nop 0
	global_load_lds_dwordx4 v130, s[26:27]
	s_waitcnt vmcnt(8)
	s_waitcnt lgkmcnt(0)
	s_barrier
	s_setprio 1
	v_mfma_f32_16x16x32_bf16 v[124:127], v[138:141], v[176:179], v[124:127]
	v_mfma_f32_16x16x32_bf16 v[120:123], v[152:155], v[176:179], v[120:123]
	v_mfma_f32_16x16x32_bf16 v[108:111], v[138:141], v[184:187], v[108:111]
	v_mfma_f32_16x16x32_bf16 v[104:107], v[152:155], v[184:187], v[104:107]
	v_mfma_f32_16x16x32_bf16 v[92:95], v[138:141], v[192:195], v[92:95]
	v_mfma_f32_16x16x32_bf16 v[88:91], v[152:155], v[192:195], v[88:91]
	v_mfma_f32_16x16x32_bf16 v[76:79], v[138:141], v[200:203], v[76:79]
	v_mfma_f32_16x16x32_bf16 v[72:75], v[152:155], v[200:203], v[72:75]
	v_mfma_f32_16x16x32_bf16 v[124:127], v[148:151], v[180:183], v[124:127]
	v_mfma_f32_16x16x32_bf16 v[120:123], v[156:159], v[180:183], v[120:123]
	v_mfma_f32_16x16x32_bf16 v[108:111], v[148:151], v[188:191], v[108:111]
	v_mfma_f32_16x16x32_bf16 v[104:107], v[156:159], v[188:191], v[104:107]
	v_mfma_f32_16x16x32_bf16 v[92:95], v[148:151], v[196:199], v[92:95]
	v_mfma_f32_16x16x32_bf16 v[88:91], v[156:159], v[196:199], v[88:91]
	v_mfma_f32_16x16x32_bf16 v[76:79], v[148:151], v[204:207], v[76:79]
	v_mfma_f32_16x16x32_bf16 v[72:75], v[156:159], v[204:207], v[72:75]
	v_mfma_f32_16x16x32_bf16 v[116:119], v[160:163], v[176:179], v[116:119]
	v_mfma_f32_16x16x32_bf16 v[112:115], v[168:171], v[176:179], v[112:115]
	v_mfma_f32_16x16x32_bf16 v[100:103], v[160:163], v[184:187], v[100:103]
	v_mfma_f32_16x16x32_bf16 v[96:99], v[168:171], v[184:187], v[96:99]
	v_mfma_f32_16x16x32_bf16 v[84:87], v[160:163], v[192:195], v[84:87]
	v_mfma_f32_16x16x32_bf16 v[80:83], v[168:171], v[192:195], v[80:83]
	v_mfma_f32_16x16x32_bf16 v[68:71], v[160:163], v[200:203], v[68:71]
	v_mfma_f32_16x16x32_bf16 v[64:67], v[168:171], v[200:203], v[64:67]
	v_mfma_f32_16x16x32_bf16 v[116:119], v[164:167], v[180:183], v[116:119]
	v_mfma_f32_16x16x32_bf16 v[112:115], v[172:175], v[180:183], v[112:115]
	v_mfma_f32_16x16x32_bf16 v[100:103], v[164:167], v[188:191], v[100:103]
	v_mfma_f32_16x16x32_bf16 v[96:99], v[172:175], v[188:191], v[96:99]
	v_mfma_f32_16x16x32_bf16 v[84:87], v[164:167], v[196:199], v[84:87]
	v_mfma_f32_16x16x32_bf16 v[80:83], v[172:175], v[196:199], v[80:83]
	v_mfma_f32_16x16x32_bf16 v[68:71], v[164:167], v[204:207], v[68:71]
	v_mfma_f32_16x16x32_bf16 v[64:67], v[172:175], v[204:207], v[64:67]
	s_setprio 0
	s_barrier
	s_add_i32 s10, s10, s30
	v_lshl_add_u64 v[142:143], v[142:143], 0, s[94:95]
	s_mov_b32 m0, s10
	ds_read_b128 v[176:179], v147 offset:49152
	ds_read_b128 v[180:183], v147 offset:50176
	ds_read_b128 v[184:187], v147 offset:51200
	ds_read_b128 v[188:191], v147 offset:52224
	ds_read_b128 v[192:195], v147 offset:53248
	ds_read_b128 v[196:199], v147 offset:54272
	ds_read_b128 v[200:203], v147 offset:55296
	ds_read_b128 v[204:207], v147 offset:56320
	global_load_lds_dwordx4 v[142:143], off
	s_add_i32 m0, s10, 0x2000
	s_add_u32 s24, s24, 0x40080
	v_lshl_add_u64 v[142:143], v[222:223], 0, s[94:95]
	s_addc_u32 s25, s25, 0
	s_add_i32 s10, s11, s30
	global_load_lds_dwordx4 v[142:143], off
	s_mov_b32 m0, s10
	s_nop 0
	global_load_lds_dwordx4 v208, s[24:25]
	v_lshl_add_u64 v[142:143], s[24:25], 0, v[128:129]
	s_add_i32 m0, s10, 0x2000
	s_nop 0
	global_load_lds_dwordx4 v[142:143], off
	v_lshl_add_u64 v[142:143], v[224:225], 0, s[94:95]
	s_mov_b32 m0, s37
	s_nop 0
	global_load_lds_dwordx4 v[142:143], off
	v_lshl_add_u64 v[142:143], v[236:237], 0, s[94:95]
	s_mov_b32 m0, s40
	s_nop 0
	global_load_lds_dwordx4 v[142:143], off
	s_waitcnt vmcnt(8)
	s_waitcnt lgkmcnt(0)
	s_barrier
	s_setprio 1
	v_mfma_f32_16x16x32_bf16 v[60:63], v[138:141], v[176:179], v[60:63]
	v_mfma_f32_16x16x32_bf16 v[56:59], v[152:155], v[176:179], v[56:59]
	v_mfma_f32_16x16x32_bf16 v[44:47], v[138:141], v[184:187], v[44:47]
	v_mfma_f32_16x16x32_bf16 v[40:43], v[152:155], v[184:187], v[40:43]
	v_mfma_f32_16x16x32_bf16 v[28:31], v[138:141], v[192:195], v[28:31]
	v_mfma_f32_16x16x32_bf16 v[24:27], v[152:155], v[192:195], v[24:27]
	v_mfma_f32_16x16x32_bf16 v[12:15], v[138:141], v[200:203], v[12:15]
	v_mfma_f32_16x16x32_bf16 v[8:11], v[152:155], v[200:203], v[8:11]
	v_mfma_f32_16x16x32_bf16 v[60:63], v[148:151], v[180:183], v[60:63]
	v_mfma_f32_16x16x32_bf16 v[56:59], v[156:159], v[180:183], v[56:59]
	v_mfma_f32_16x16x32_bf16 v[44:47], v[148:151], v[188:191], v[44:47]
	v_mfma_f32_16x16x32_bf16 v[40:43], v[156:159], v[188:191], v[40:43]
	v_mfma_f32_16x16x32_bf16 v[28:31], v[148:151], v[196:199], v[28:31]
	v_mfma_f32_16x16x32_bf16 v[24:27], v[156:159], v[196:199], v[24:27]
	v_mfma_f32_16x16x32_bf16 v[12:15], v[148:151], v[204:207], v[12:15]
	v_mfma_f32_16x16x32_bf16 v[8:11], v[156:159], v[204:207], v[8:11]
	v_mfma_f32_16x16x32_bf16 v[52:55], v[160:163], v[176:179], v[52:55]
	v_mfma_f32_16x16x32_bf16 v[48:51], v[168:171], v[176:179], v[48:51]
	v_mfma_f32_16x16x32_bf16 v[36:39], v[160:163], v[184:187], v[36:39]
	v_mfma_f32_16x16x32_bf16 v[32:35], v[168:171], v[184:187], v[32:35]
	v_mfma_f32_16x16x32_bf16 v[20:23], v[160:163], v[192:195], v[20:23]
	v_mfma_f32_16x16x32_bf16 v[16:19], v[168:171], v[192:195], v[16:19]
	v_mfma_f32_16x16x32_bf16 v[4:7], v[160:163], v[200:203], v[4:7]
	v_mfma_f32_16x16x32_bf16 v[0:3], v[168:171], v[200:203], v[0:3]
	v_mfma_f32_16x16x32_bf16 v[52:55], v[164:167], v[180:183], v[52:55]
	v_mfma_f32_16x16x32_bf16 v[48:51], v[172:175], v[180:183], v[48:51]
	v_mfma_f32_16x16x32_bf16 v[36:39], v[164:167], v[188:191], v[36:39]
	v_mfma_f32_16x16x32_bf16 v[32:35], v[172:175], v[188:191], v[32:35]
	v_mfma_f32_16x16x32_bf16 v[20:23], v[164:167], v[196:199], v[20:23]
	v_mfma_f32_16x16x32_bf16 v[16:19], v[172:175], v[196:199], v[16:19]
	v_mfma_f32_16x16x32_bf16 v[4:7], v[164:167], v[204:207], v[4:7]
	v_mfma_f32_16x16x32_bf16 v[0:3], v[172:175], v[204:207], v[0:3]
	s_setprio 0
	s_barrier
	s_add_i32 s92, s92, 2
	s_add_u32 s22, s22, 0x100
	s_addc_u32 s23, s23, 0
	s_add_u32 s82, s82, 0x100
	s_addc_u32 s83, s83, 0
	s_cmp_gt_u32 s92, 13
	s_cbranch_scc0 .LBB0_710
	v_lshl_add_u32 v140, s43, 8, v144
	v_lshl_or_b32 v138, s42, 8, v146
	v_lshlrev_b32_e32 v139, 2, v140
	v_lshlrev_b32_e32 v140, 11, v140
	v_lshl_add_u32 v138, v138, 1, v140
	s_mov_b64 s[100:101], s[46:47]
	global_load_dwordx4 v[148:151], v138, s[100:101]
	global_load_dwordx4 v[152:155], v138, s[100:101] offset:256
	s_add_u32 s100, s100, 0x8000
	s_addc_u32 s101, s101, 0
	global_load_dwordx4 v[156:159], v138, s[100:101]
	global_load_dwordx4 v[160:163], v138, s[100:101] offset:256
	s_add_u32 s100, s100, 0x8000
	s_addc_u32 s101, s101, 0
	global_load_dwordx4 v[164:167], v138, s[100:101]
	global_load_dwordx4 v[168:171], v138, s[100:101] offset:256
	s_add_u32 s100, s100, 0x8000
	s_addc_u32 s101, s101, 0
	global_load_dwordx4 v[172:175], v138, s[100:101]
	global_load_dwordx4 v[176:179], v138, s[100:101] offset:256
	s_add_u32 s100, s100, 0x28000
	s_addc_u32 s101, s101, 0
	global_load_dwordx4 v[180:183], v138, s[100:101]
	global_load_dwordx4 v[184:187], v138, s[100:101] offset:256
	s_add_u32 s100, s100, 0x8000
	s_addc_u32 s101, s101, 0
	global_load_dwordx4 v[188:191], v138, s[100:101]
	global_load_dwordx4 v[192:195], v138, s[100:101] offset:256
	s_add_u32 s100, s100, 0x8000
	s_addc_u32 s101, s101, 0
	global_load_dwordx4 v[196:199], v138, s[100:101]
	global_load_dwordx4 v[200:203], v138, s[100:101] offset:256
	s_add_u32 s100, s100, 0x8000
	s_addc_u32 s101, s101, 0
	global_load_dwordx4 v[204:207], v138, s[100:101]
	global_load_dwordx4 v[236:239], v138, s[100:101] offset:256
	s_and_b64 vcc, exec, s[12:13]
	s_cbranch_vccz .LBB0_713
	s_barrier

.LBB0_795:
	s_add_u32 s10, s20, 0xfffc0080
	s_addc_u32 s11, s21, -1
	s_add_i32 s83, 0, 0x10000
	s_cmp_eq_u32 s82, 12
	s_cselect_b32 s25, s15, s11
	s_cselect_b32 s24, s42, s10
	v_add_u32_e32 v138, s83, v141
	s_cselect_b32 s23, s13, s80
	s_cselect_b32 s22, s43, s70
	s_add_i32 s10, 0, 0x14000
	ds_read_b128 v[144:147], v138
	ds_read_b128 v[148:151], v138 offset:1024
	ds_read_b128 v[152:155], v138 offset:2048
	ds_read_b128 v[156:159], v138 offset:3072
	v_add_u32_e32 v138, s10, v141
	ds_read_b128 v[160:163], v138
	ds_read_b128 v[164:167], v138 offset:1024
	ds_read_b128 v[168:171], v138 offset:2048
	ds_read_b128 v[172:175], v138 offset:3072
	s_add_i32 m0, s29, 0xc000
	ds_read_b128 v[176:179], v143
	ds_read_b128 v[180:183], v143 offset:1024
	ds_read_b128 v[184:187], v143 offset:2048
	ds_read_b128 v[188:191], v143 offset:3072
	ds_read_b128 v[192:195], v143 offset:4096
	ds_read_b128 v[196:199], v143 offset:5120
	ds_read_b128 v[200:203], v143 offset:6144
	ds_read_b128 v[204:207], v143 offset:7168
	global_load_lds_dwordx4 v134, s[20:21]
	s_add_i32 m0, s29, 0xe000
	s_nop 0
	global_load_lds_dwordx4 v136, s[20:21]
	s_waitcnt vmcnt(8)
	s_waitcnt lgkmcnt(0)
	s_barrier
	s_setprio 1
	v_mfma_f32_16x16x32_bf16 v[124:127], v[144:147], v[176:179], v[124:127]
	v_mfma_f32_16x16x32_bf16 v[120:123], v[152:155], v[176:179], v[120:123]
	v_mfma_f32_16x16x32_bf16 v[108:111], v[144:147], v[184:187], v[108:111]
	v_mfma_f32_16x16x32_bf16 v[104:107], v[152:155], v[184:187], v[104:107]
	v_mfma_f32_16x16x32_bf16 v[92:95], v[144:147], v[192:195], v[92:95]
	v_mfma_f32_16x16x32_bf16 v[88:91], v[152:155], v[192:195], v[88:91]
	v_mfma_f32_16x16x32_bf16 v[76:79], v[144:147], v[200:203], v[76:79]
	v_mfma_f32_16x16x32_bf16 v[72:75], v[152:155], v[200:203], v[72:75]
	v_mfma_f32_16x16x32_bf16 v[124:127], v[148:151], v[180:183], v[124:127]
	v_mfma_f32_16x16x32_bf16 v[120:123], v[156:159], v[180:183], v[120:123]
	v_mfma_f32_16x16x32_bf16 v[108:111], v[148:151], v[188:191], v[108:111]
	v_mfma_f32_16x16x32_bf16 v[104:107], v[156:159], v[188:191], v[104:107]
	v_mfma_f32_16x16x32_bf16 v[92:95], v[148:151], v[196:199], v[92:95]
	v_mfma_f32_16x16x32_bf16 v[88:91], v[156:159], v[196:199], v[88:91]
	v_mfma_f32_16x16x32_bf16 v[76:79], v[148:151], v[204:207], v[76:79]
	v_mfma_f32_16x16x32_bf16 v[72:75], v[156:159], v[204:207], v[72:75]
	v_mfma_f32_16x16x32_bf16 v[116:119], v[160:163], v[176:179], v[116:119]
	v_mfma_f32_16x16x32_bf16 v[112:115], v[168:171], v[176:179], v[112:115]
	v_mfma_f32_16x16x32_bf16 v[100:103], v[160:163], v[184:187], v[100:103]
	v_mfma_f32_16x16x32_bf16 v[96:99], v[168:171], v[184:187], v[96:99]
	v_mfma_f32_16x16x32_bf16 v[84:87], v[160:163], v[192:195], v[84:87]
	v_mfma_f32_16x16x32_bf16 v[80:83], v[168:171], v[192:195], v[80:83]
	v_mfma_f32_16x16x32_bf16 v[68:71], v[160:163], v[200:203], v[68:71]
	v_mfma_f32_16x16x32_bf16 v[64:67], v[168:171], v[200:203], v[64:67]
	v_mfma_f32_16x16x32_bf16 v[116:119], v[164:167], v[180:183], v[116:119]
	v_mfma_f32_16x16x32_bf16 v[112:115], v[172:175], v[180:183], v[112:115]
	v_mfma_f32_16x16x32_bf16 v[100:103], v[164:167], v[188:191], v[100:103]
	v_mfma_f32_16x16x32_bf16 v[96:99], v[172:175], v[188:191], v[96:99]
	v_mfma_f32_16x16x32_bf16 v[84:87], v[164:167], v[196:199], v[84:87]
	v_mfma_f32_16x16x32_bf16 v[80:83], v[172:175], v[196:199], v[80:83]
	v_mfma_f32_16x16x32_bf16 v[68:71], v[164:167], v[204:207], v[68:71]
	v_mfma_f32_16x16x32_bf16 v[64:67], v[172:175], v[204:207], v[64:67]
	s_setprio 0
	s_barrier
	s_add_i32 s11, s83, s28
	v_lshl_add_u64 v[138:139], s[22:23], 0, v[208:209]
	s_mov_b32 m0, s11
	ds_read_b128 v[176:179], v143 offset:16384
	ds_read_b128 v[180:183], v143 offset:17408
	ds_read_b128 v[184:187], v143 offset:18432
	ds_read_b128 v[188:191], v143 offset:19456
	ds_read_b128 v[192:195], v143 offset:20480
	ds_read_b128 v[196:199], v143 offset:21504
	ds_read_b128 v[200:203], v143 offset:22528
	ds_read_b128 v[204:207], v143 offset:23552
	global_load_lds_dwordx4 v[138:139], off
	s_add_i32 m0, s11, 0x2000
	s_add_u32 vcc_lo, s22, 0x40000
	v_lshl_add_u64 v[222:223], s[22:23], 0, v[128:129]
	s_addc_u32 vcc_hi, s23, 0
	s_add_i32 s10, s10, s28
	global_load_lds_dwordx4 v[222:223], off
	s_mov_b32 m0, s10
	v_lshl_add_u64 v[236:237], s[24:25], 0, v[130:131]
	global_load_lds_dwordx4 v208, vcc
	s_add_i32 m0, s10, 0x2000
	s_nop 0
	global_load_lds_dwordx4 v128, vcc
	v_lshl_add_u64 v[224:225], s[24:25], 0, v[132:133]
	s_mov_b32 m0, s29
	s_nop 0
	global_load_lds_dwordx4 v[224:225], off
	s_mov_b32 m0, s30
	s_nop 0
	global_load_lds_dwordx4 v[236:237], off
	s_waitcnt vmcnt(8)
	s_waitcnt lgkmcnt(0)
	s_barrier
	s_setprio 1
	v_mfma_f32_16x16x32_bf16 v[60:63], v[144:147], v[176:179], v[60:63]
	v_mfma_f32_16x16x32_bf16 v[56:59], v[152:155], v[176:179], v[56:59]
	v_mfma_f32_16x16x32_bf16 v[44:47], v[144:147], v[184:187], v[44:47]
	v_mfma_f32_16x16x32_bf16 v[40:43], v[152:155], v[184:187], v[40:43]
	v_mfma_f32_16x16x32_bf16 v[28:31], v[144:147], v[192:195], v[28:31]
	v_mfma_f32_16x16x32_bf16 v[24:27], v[152:155], v[192:195], v[24:27]
	v_mfma_f32_16x16x32_bf16 v[12:15], v[144:147], v[200:203], v[12:15]
	v_mfma_f32_16x16x32_bf16 v[8:11], v[152:155], v[200:203], v[8:11]
	v_mfma_f32_16x16x32_bf16 v[60:63], v[148:151], v[180:183], v[60:63]
	v_mfma_f32_16x16x32_bf16 v[56:59], v[156:159], v[180:183], v[56:59]
	v_mfma_f32_16x16x32_bf16 v[44:47], v[148:151], v[188:191], v[44:47]
	v_mfma_f32_16x16x32_bf16 v[40:43], v[156:159], v[188:191], v[40:43]
	v_mfma_f32_16x16x32_bf16 v[28:31], v[148:151], v[196:199], v[28:31]
	v_mfma_f32_16x16x32_bf16 v[24:27], v[156:159], v[196:199], v[24:27]
	v_mfma_f32_16x16x32_bf16 v[12:15], v[148:151], v[204:207], v[12:15]
	v_mfma_f32_16x16x32_bf16 v[8:11], v[156:159], v[204:207], v[8:11]
	v_mfma_f32_16x16x32_bf16 v[52:55], v[160:163], v[176:179], v[52:55]
	v_mfma_f32_16x16x32_bf16 v[48:51], v[168:171], v[176:179], v[48:51]
	v_mfma_f32_16x16x32_bf16 v[36:39], v[160:163], v[184:187], v[36:39]
	v_mfma_f32_16x16x32_bf16 v[32:35], v[168:171], v[184:187], v[32:35]
	v_mfma_f32_16x16x32_bf16 v[20:23], v[160:163], v[192:195], v[20:23]
	v_mfma_f32_16x16x32_bf16 v[16:19], v[168:171], v[192:195], v[16:19]
	v_mfma_f32_16x16x32_bf16 v[4:7], v[160:163], v[200:203], v[4:7]
	v_mfma_f32_16x16x32_bf16 v[0:3], v[168:171], v[200:203], v[0:3]
	v_mfma_f32_16x16x32_bf16 v[52:55], v[164:167], v[180:183], v[52:55]
	v_mfma_f32_16x16x32_bf16 v[48:51], v[172:175], v[180:183], v[48:51]
	v_mfma_f32_16x16x32_bf16 v[36:39], v[164:167], v[188:191], v[36:39]
	v_mfma_f32_16x16x32_bf16 v[32:35], v[172:175], v[188:191], v[32:35]
	v_mfma_f32_16x16x32_bf16 v[20:23], v[164:167], v[196:199], v[20:23]
	v_mfma_f32_16x16x32_bf16 v[16:19], v[172:175], v[196:199], v[16:19]
	v_mfma_f32_16x16x32_bf16 v[4:7], v[164:167], v[204:207], v[4:7]
	v_mfma_f32_16x16x32_bf16 v[0:3], v[172:175], v[204:207], v[0:3]
	s_setprio 0
	s_barrier
	s_add_i32 s10, 0, 0x18000
	s_add_i32 s11, 0, 0x1c000
	v_add_u32_e32 v156, s10, v141
	v_add_u32_e32 v172, s11, v141
	ds_read_b128 v[144:147], v156
	ds_read_b128 v[148:151], v156 offset:1024
	ds_read_b128 v[152:155], v156 offset:2048
	ds_read_b128 v[156:159], v156 offset:3072
	ds_read_b128 v[160:163], v172
	ds_read_b128 v[164:167], v172 offset:1024
	ds_read_b128 v[168:171], v172 offset:2048
	ds_read_b128 v[172:175], v172 offset:3072
	s_add_u32 s24, s24, 0x40000
	s_addc_u32 s25, s25, 0
	s_mov_b32 m0, s31
	ds_read_b128 v[176:179], v143 offset:32768
	ds_read_b128 v[180:183], v143 offset:33792
	ds_read_b128 v[184:187], v143 offset:34816
	ds_read_b128 v[188:191], v143 offset:35840
	ds_read_b128 v[192:195], v143 offset:36864
	ds_read_b128 v[196:199], v143 offset:37888
	ds_read_b128 v[200:203], v143 offset:38912
	ds_read_b128 v[204:207], v143 offset:39936
	global_load_lds_dwordx4 v132, s[24:25]
	s_mov_b32 m0, s34
	s_nop 0
	global_load_lds_dwordx4 v130, s[24:25]
	s_waitcnt vmcnt(8)
	s_waitcnt lgkmcnt(0)
	s_barrier
	s_setprio 1
	v_mfma_f32_16x16x32_bf16 v[124:127], v[144:147], v[176:179], v[124:127]
	v_mfma_f32_16x16x32_bf16 v[120:123], v[152:155], v[176:179], v[120:123]
	v_mfma_f32_16x16x32_bf16 v[108:111], v[144:147], v[184:187], v[108:111]
	v_mfma_f32_16x16x32_bf16 v[104:107], v[152:155], v[184:187], v[104:107]
	v_mfma_f32_16x16x32_bf16 v[92:95], v[144:147], v[192:195], v[92:95]
	v_mfma_f32_16x16x32_bf16 v[88:91], v[152:155], v[192:195], v[88:91]
	v_mfma_f32_16x16x32_bf16 v[76:79], v[144:147], v[200:203], v[76:79]
	v_mfma_f32_16x16x32_bf16 v[72:75], v[152:155], v[200:203], v[72:75]
	v_mfma_f32_16x16x32_bf16 v[124:127], v[148:151], v[180:183], v[124:127]
	v_mfma_f32_16x16x32_bf16 v[120:123], v[156:159], v[180:183], v[120:123]
	v_mfma_f32_16x16x32_bf16 v[108:111], v[148:151], v[188:191], v[108:111]
	v_mfma_f32_16x16x32_bf16 v[104:107], v[156:159], v[188:191], v[104:107]
	v_mfma_f32_16x16x32_bf16 v[92:95], v[148:151], v[196:199], v[92:95]
	v_mfma_f32_16x16x32_bf16 v[88:91], v[156:159], v[196:199], v[88:91]
	v_mfma_f32_16x16x32_bf16 v[76:79], v[148:151], v[204:207], v[76:79]
	v_mfma_f32_16x16x32_bf16 v[72:75], v[156:159], v[204:207], v[72:75]
	v_mfma_f32_16x16x32_bf16 v[116:119], v[160:163], v[176:179], v[116:119]
	v_mfma_f32_16x16x32_bf16 v[112:115], v[168:171], v[176:179], v[112:115]
	v_mfma_f32_16x16x32_bf16 v[100:103], v[160:163], v[184:187], v[100:103]
	v_mfma_f32_16x16x32_bf16 v[96:99], v[168:171], v[184:187], v[96:99]
	v_mfma_f32_16x16x32_bf16 v[84:87], v[160:163], v[192:195], v[84:87]
	v_mfma_f32_16x16x32_bf16 v[80:83], v[168:171], v[192:195], v[80:83]
	v_mfma_f32_16x16x32_bf16 v[68:71], v[160:163], v[200:203], v[68:71]
	v_mfma_f32_16x16x32_bf16 v[64:67], v[168:171], v[200:203], v[64:67]
	v_mfma_f32_16x16x32_bf16 v[116:119], v[164:167], v[180:183], v[116:119]
	v_mfma_f32_16x16x32_bf16 v[112:115], v[172:175], v[180:183], v[112:115]
	v_mfma_f32_16x16x32_bf16 v[100:103], v[164:167], v[188:191], v[100:103]
	v_mfma_f32_16x16x32_bf16 v[96:99], v[172:175], v[188:191], v[96:99]
	v_mfma_f32_16x16x32_bf16 v[84:87], v[164:167], v[196:199], v[84:87]
	v_mfma_f32_16x16x32_bf16 v[80:83], v[172:175], v[196:199], v[80:83]
	v_mfma_f32_16x16x32_bf16 v[68:71], v[164:167], v[204:207], v[68:71]
	v_mfma_f32_16x16x32_bf16 v[64:67], v[172:175], v[204:207], v[64:67]
	s_setprio 0
	s_barrier
	s_add_i32 s10, s10, s28
	v_lshl_add_u64 v[138:139], v[138:139], 0, s[94:95]
	s_mov_b32 m0, s10
	ds_read_b128 v[176:179], v143 offset:49152
	ds_read_b128 v[180:183], v143 offset:50176
	ds_read_b128 v[184:187], v143 offset:51200
	ds_read_b128 v[188:191], v143 offset:52224
	ds_read_b128 v[192:195], v143 offset:53248
	ds_read_b128 v[196:199], v143 offset:54272
	ds_read_b128 v[200:203], v143 offset:55296
	ds_read_b128 v[204:207], v143 offset:56320
	global_load_lds_dwordx4 v[138:139], off
	s_add_i32 m0, s10, 0x2000
	s_add_u32 s22, s22, 0x40080
	v_lshl_add_u64 v[138:139], v[222:223], 0, s[94:95]
	s_addc_u32 s23, s23, 0
	s_add_i32 s10, s11, s28
	global_load_lds_dwordx4 v[138:139], off
	s_mov_b32 m0, s10
	s_nop 0
	global_load_lds_dwordx4 v208, s[22:23]
	v_lshl_add_u64 v[138:139], s[22:23], 0, v[128:129]
	s_add_i32 m0, s10, 0x2000
	s_nop 0
	global_load_lds_dwordx4 v[138:139], off
	v_lshl_add_u64 v[138:139], v[224:225], 0, s[94:95]
	s_mov_b32 m0, s35
	s_nop 0
	global_load_lds_dwordx4 v[138:139], off
	v_lshl_add_u64 v[138:139], v[236:237], 0, s[94:95]
	s_mov_b32 m0, s36
	s_nop 0
	global_load_lds_dwordx4 v[138:139], off
	s_waitcnt vmcnt(8)
	s_waitcnt lgkmcnt(0)
	s_barrier
	s_setprio 1
	v_mfma_f32_16x16x32_bf16 v[60:63], v[144:147], v[176:179], v[60:63]
	v_mfma_f32_16x16x32_bf16 v[56:59], v[152:155], v[176:179], v[56:59]
	v_mfma_f32_16x16x32_bf16 v[44:47], v[144:147], v[184:187], v[44:47]
	v_mfma_f32_16x16x32_bf16 v[40:43], v[152:155], v[184:187], v[40:43]
	v_mfma_f32_16x16x32_bf16 v[28:31], v[144:147], v[192:195], v[28:31]
	v_mfma_f32_16x16x32_bf16 v[24:27], v[152:155], v[192:195], v[24:27]
	v_mfma_f32_16x16x32_bf16 v[12:15], v[144:147], v[200:203], v[12:15]
	v_mfma_f32_16x16x32_bf16 v[8:11], v[152:155], v[200:203], v[8:11]
	v_mfma_f32_16x16x32_bf16 v[60:63], v[148:151], v[180:183], v[60:63]
	v_mfma_f32_16x16x32_bf16 v[56:59], v[156:159], v[180:183], v[56:59]
	v_mfma_f32_16x16x32_bf16 v[44:47], v[148:151], v[188:191], v[44:47]
	v_mfma_f32_16x16x32_bf16 v[40:43], v[156:159], v[188:191], v[40:43]
	v_mfma_f32_16x16x32_bf16 v[28:31], v[148:151], v[196:199], v[28:31]
	v_mfma_f32_16x16x32_bf16 v[24:27], v[156:159], v[196:199], v[24:27]
	v_mfma_f32_16x16x32_bf16 v[12:15], v[148:151], v[204:207], v[12:15]
	v_mfma_f32_16x16x32_bf16 v[8:11], v[156:159], v[204:207], v[8:11]
	v_mfma_f32_16x16x32_bf16 v[52:55], v[160:163], v[176:179], v[52:55]
	v_mfma_f32_16x16x32_bf16 v[48:51], v[168:171], v[176:179], v[48:51]
	v_mfma_f32_16x16x32_bf16 v[36:39], v[160:163], v[184:187], v[36:39]
	v_mfma_f32_16x16x32_bf16 v[32:35], v[168:171], v[184:187], v[32:35]
	v_mfma_f32_16x16x32_bf16 v[20:23], v[160:163], v[192:195], v[20:23]
	v_mfma_f32_16x16x32_bf16 v[16:19], v[168:171], v[192:195], v[16:19]
	v_mfma_f32_16x16x32_bf16 v[4:7], v[160:163], v[200:203], v[4:7]
	v_mfma_f32_16x16x32_bf16 v[0:3], v[168:171], v[200:203], v[0:3]
	v_mfma_f32_16x16x32_bf16 v[52:55], v[164:167], v[180:183], v[52:55]
	v_mfma_f32_16x16x32_bf16 v[48:51], v[172:175], v[180:183], v[48:51]
	v_mfma_f32_16x16x32_bf16 v[36:39], v[164:167], v[188:191], v[36:39]
	v_mfma_f32_16x16x32_bf16 v[32:35], v[172:175], v[188:191], v[32:35]
	v_mfma_f32_16x16x32_bf16 v[20:23], v[164:167], v[196:199], v[20:23]
	v_mfma_f32_16x16x32_bf16 v[16:19], v[172:175], v[196:199], v[16:19]
	v_mfma_f32_16x16x32_bf16 v[4:7], v[164:167], v[204:207], v[4:7]
	v_mfma_f32_16x16x32_bf16 v[0:3], v[172:175], v[204:207], v[0:3]
	s_setprio 0
	s_barrier
	s_add_i32 s82, s82, 2
	s_add_u32 s20, s20, 0x100
	s_addc_u32 s21, s21, 0
	s_add_u32 s70, s70, 0x100
	s_addc_u32 s80, s80, 0
	s_cmp_gt_u32 s82, 13
	s_cbranch_scc0 .LBB0_795
	v_lshl_add_u32 v138, s40, 8, v140
	v_ashrrev_i32_e32 v139, 31, v138
	v_lshl_add_u64 v[146:147], v[138:139], 2, s[76:77]
	global_load_dword v160, v[146:147], off
	global_load_dword v161, v[146:147], off offset:64
	global_load_dword v162, v[146:147], off offset:128
	global_load_dword v163, v[146:147], off offset:192
	global_load_dword v164, v[146:147], off offset:512
	global_load_dword v165, v[146:147], off offset:576
	global_load_dword v166, v[146:147], off offset:640
	global_load_dword v167, v[146:147], off offset:704
	s_and_b64 vcc, exec, s[6:7]
	s_cbranch_vccz .LBB0_798
	s_barrier

.LBB0_869:
	s_add_u32 s10, s24, 0xfff00080
	s_addc_u32 s11, s25, -1
	s_add_i32 s83, 0, 0x10000
	s_cmp_eq_u32 s82, 60
	s_cselect_b32 s29, s19, s11
	s_cselect_b32 s28, s72, s10
	v_add_u32_e32 v142, s83, v145
	s_cselect_b32 s27, s17, s80
	s_cselect_b32 s26, s76, s77
	s_add_i32 s10, 0, 0x14000
	ds_read_b128 v[138:141], v142
	ds_read_b128 v[148:151], v142 offset:1024
	ds_read_b128 v[152:155], v142 offset:2048
	ds_read_b128 v[156:159], v142 offset:3072
	v_add_u32_e32 v142, s10, v145
	ds_read_b128 v[160:163], v142
	ds_read_b128 v[164:167], v142 offset:1024
	ds_read_b128 v[168:171], v142 offset:2048
	ds_read_b128 v[172:175], v142 offset:3072
	s_add_i32 m0, s34, 0xc000
	ds_read_b128 v[176:179], v147
	ds_read_b128 v[180:183], v147 offset:1024
	ds_read_b128 v[184:187], v147 offset:2048
	ds_read_b128 v[188:191], v147 offset:3072
	ds_read_b128 v[192:195], v147 offset:4096
	ds_read_b128 v[196:199], v147 offset:5120
	ds_read_b128 v[200:203], v147 offset:6144
	ds_read_b128 v[204:207], v147 offset:7168
	global_load_lds_dwordx4 v134, s[24:25]
	s_add_i32 m0, s34, 0xe000
	s_nop 0
	global_load_lds_dwordx4 v136, s[24:25]
	s_waitcnt vmcnt(8)
	s_waitcnt lgkmcnt(0)
	s_barrier
	s_setprio 1
	v_mfma_f32_16x16x32_bf16 v[124:127], v[138:141], v[176:179], v[124:127]
	v_mfma_f32_16x16x32_bf16 v[120:123], v[152:155], v[176:179], v[120:123]
	v_mfma_f32_16x16x32_bf16 v[108:111], v[138:141], v[184:187], v[108:111]
	v_mfma_f32_16x16x32_bf16 v[104:107], v[152:155], v[184:187], v[104:107]
	v_mfma_f32_16x16x32_bf16 v[92:95], v[138:141], v[192:195], v[92:95]
	v_mfma_f32_16x16x32_bf16 v[88:91], v[152:155], v[192:195], v[88:91]
	v_mfma_f32_16x16x32_bf16 v[76:79], v[138:141], v[200:203], v[76:79]
	v_mfma_f32_16x16x32_bf16 v[72:75], v[152:155], v[200:203], v[72:75]
	v_mfma_f32_16x16x32_bf16 v[124:127], v[148:151], v[180:183], v[124:127]
	v_mfma_f32_16x16x32_bf16 v[120:123], v[156:159], v[180:183], v[120:123]
	v_mfma_f32_16x16x32_bf16 v[108:111], v[148:151], v[188:191], v[108:111]
	v_mfma_f32_16x16x32_bf16 v[104:107], v[156:159], v[188:191], v[104:107]
	v_mfma_f32_16x16x32_bf16 v[92:95], v[148:151], v[196:199], v[92:95]
	v_mfma_f32_16x16x32_bf16 v[88:91], v[156:159], v[196:199], v[88:91]
	v_mfma_f32_16x16x32_bf16 v[76:79], v[148:151], v[204:207], v[76:79]
	v_mfma_f32_16x16x32_bf16 v[72:75], v[156:159], v[204:207], v[72:75]
	v_mfma_f32_16x16x32_bf16 v[116:119], v[160:163], v[176:179], v[116:119]
	v_mfma_f32_16x16x32_bf16 v[112:115], v[168:171], v[176:179], v[112:115]
	v_mfma_f32_16x16x32_bf16 v[100:103], v[160:163], v[184:187], v[100:103]
	v_mfma_f32_16x16x32_bf16 v[96:99], v[168:171], v[184:187], v[96:99]
	v_mfma_f32_16x16x32_bf16 v[84:87], v[160:163], v[192:195], v[84:87]
	v_mfma_f32_16x16x32_bf16 v[80:83], v[168:171], v[192:195], v[80:83]
	v_mfma_f32_16x16x32_bf16 v[68:71], v[160:163], v[200:203], v[68:71]
	v_mfma_f32_16x16x32_bf16 v[64:67], v[168:171], v[200:203], v[64:67]
	v_mfma_f32_16x16x32_bf16 v[116:119], v[164:167], v[180:183], v[116:119]
	v_mfma_f32_16x16x32_bf16 v[112:115], v[172:175], v[180:183], v[112:115]
	v_mfma_f32_16x16x32_bf16 v[100:103], v[164:167], v[188:191], v[100:103]
	v_mfma_f32_16x16x32_bf16 v[96:99], v[172:175], v[188:191], v[96:99]
	v_mfma_f32_16x16x32_bf16 v[84:87], v[164:167], v[196:199], v[84:87]
	v_mfma_f32_16x16x32_bf16 v[80:83], v[172:175], v[196:199], v[80:83]
	v_mfma_f32_16x16x32_bf16 v[68:71], v[164:167], v[204:207], v[68:71]
	v_mfma_f32_16x16x32_bf16 v[64:67], v[172:175], v[204:207], v[64:67]
	s_setprio 0
	s_barrier
	s_add_i32 s11, s83, s31
	v_lshl_add_u64 v[142:143], s[26:27], 0, v[208:209]
	s_mov_b32 m0, s11
	ds_read_b128 v[176:179], v147 offset:16384
	ds_read_b128 v[180:183], v147 offset:17408
	ds_read_b128 v[184:187], v147 offset:18432
	ds_read_b128 v[188:191], v147 offset:19456
	ds_read_b128 v[192:195], v147 offset:20480
	ds_read_b128 v[196:199], v147 offset:21504
	ds_read_b128 v[200:203], v147 offset:22528
	ds_read_b128 v[204:207], v147 offset:23552
	global_load_lds_dwordx4 v[142:143], off
	s_add_i32 m0, s11, 0x2000
	s_add_u32 s96, s26, 0x100000
	v_lshl_add_u64 v[222:223], s[26:27], 0, v[128:129]
	s_addc_u32 s97, s27, 0
	s_add_i32 s10, s10, s31
	global_load_lds_dwordx4 v[222:223], off
	s_mov_b32 m0, s10
	v_lshl_add_u64 v[236:237], s[28:29], 0, v[130:131]
	global_load_lds_dwordx4 v208, s[96:97]
	s_add_i32 m0, s10, 0x2000
	s_nop 0
	global_load_lds_dwordx4 v128, s[96:97]
	v_lshl_add_u64 v[224:225], s[28:29], 0, v[132:133]
	s_mov_b32 m0, s34
	s_nop 0
	global_load_lds_dwordx4 v[224:225], off
	s_mov_b32 m0, s35
	s_nop 0
	global_load_lds_dwordx4 v[236:237], off
	s_waitcnt vmcnt(8)
	s_waitcnt lgkmcnt(0)
	s_barrier
	s_setprio 1
	v_mfma_f32_16x16x32_bf16 v[60:63], v[138:141], v[176:179], v[60:63]
	v_mfma_f32_16x16x32_bf16 v[56:59], v[152:155], v[176:179], v[56:59]
	v_mfma_f32_16x16x32_bf16 v[44:47], v[138:141], v[184:187], v[44:47]
	v_mfma_f32_16x16x32_bf16 v[40:43], v[152:155], v[184:187], v[40:43]
	v_mfma_f32_16x16x32_bf16 v[28:31], v[138:141], v[192:195], v[28:31]
	v_mfma_f32_16x16x32_bf16 v[24:27], v[152:155], v[192:195], v[24:27]
	v_mfma_f32_16x16x32_bf16 v[12:15], v[138:141], v[200:203], v[12:15]
	v_mfma_f32_16x16x32_bf16 v[8:11], v[152:155], v[200:203], v[8:11]
	v_mfma_f32_16x16x32_bf16 v[60:63], v[148:151], v[180:183], v[60:63]
	v_mfma_f32_16x16x32_bf16 v[56:59], v[156:159], v[180:183], v[56:59]
	v_mfma_f32_16x16x32_bf16 v[44:47], v[148:151], v[188:191], v[44:47]
	v_mfma_f32_16x16x32_bf16 v[40:43], v[156:159], v[188:191], v[40:43]
	v_mfma_f32_16x16x32_bf16 v[28:31], v[148:151], v[196:199], v[28:31]
	v_mfma_f32_16x16x32_bf16 v[24:27], v[156:159], v[196:199], v[24:27]
	v_mfma_f32_16x16x32_bf16 v[12:15], v[148:151], v[204:207], v[12:15]
	v_mfma_f32_16x16x32_bf16 v[8:11], v[156:159], v[204:207], v[8:11]
	v_mfma_f32_16x16x32_bf16 v[52:55], v[160:163], v[176:179], v[52:55]
	v_mfma_f32_16x16x32_bf16 v[48:51], v[168:171], v[176:179], v[48:51]
	v_mfma_f32_16x16x32_bf16 v[36:39], v[160:163], v[184:187], v[36:39]
	v_mfma_f32_16x16x32_bf16 v[32:35], v[168:171], v[184:187], v[32:35]
	v_mfma_f32_16x16x32_bf16 v[20:23], v[160:163], v[192:195], v[20:23]
	v_mfma_f32_16x16x32_bf16 v[16:19], v[168:171], v[192:195], v[16:19]
	v_mfma_f32_16x16x32_bf16 v[4:7], v[160:163], v[200:203], v[4:7]
	v_mfma_f32_16x16x32_bf16 v[0:3], v[168:171], v[200:203], v[0:3]
	v_mfma_f32_16x16x32_bf16 v[52:55], v[164:167], v[180:183], v[52:55]
	v_mfma_f32_16x16x32_bf16 v[48:51], v[172:175], v[180:183], v[48:51]
	v_mfma_f32_16x16x32_bf16 v[36:39], v[164:167], v[188:191], v[36:39]
	v_mfma_f32_16x16x32_bf16 v[32:35], v[172:175], v[188:191], v[32:35]
	v_mfma_f32_16x16x32_bf16 v[20:23], v[164:167], v[196:199], v[20:23]
	v_mfma_f32_16x16x32_bf16 v[16:19], v[172:175], v[196:199], v[16:19]
	v_mfma_f32_16x16x32_bf16 v[4:7], v[164:167], v[204:207], v[4:7]
	v_mfma_f32_16x16x32_bf16 v[0:3], v[172:175], v[204:207], v[0:3]
	s_setprio 0
	s_barrier
	s_add_i32 s10, 0, 0x18000
	s_add_i32 s11, 0, 0x1c000
	v_add_u32_e32 v156, s10, v145
	v_add_u32_e32 v172, s11, v145
	ds_read_b128 v[138:141], v156
	ds_read_b128 v[148:151], v156 offset:1024
	ds_read_b128 v[152:155], v156 offset:2048
	ds_read_b128 v[156:159], v156 offset:3072
	ds_read_b128 v[160:163], v172
	ds_read_b128 v[164:167], v172 offset:1024
	ds_read_b128 v[168:171], v172 offset:2048
	ds_read_b128 v[172:175], v172 offset:3072
	s_add_u32 s28, s28, 0x100000
	s_addc_u32 s29, s29, 0
	s_mov_b32 m0, s36
	ds_read_b128 v[176:179], v147 offset:32768
	ds_read_b128 v[180:183], v147 offset:33792
	ds_read_b128 v[184:187], v147 offset:34816
	ds_read_b128 v[188:191], v147 offset:35840
	ds_read_b128 v[192:195], v147 offset:36864
	ds_read_b128 v[196:199], v147 offset:37888
	ds_read_b128 v[200:203], v147 offset:38912
	ds_read_b128 v[204:207], v147 offset:39936
	global_load_lds_dwordx4 v132, s[28:29]
	s_mov_b32 m0, s37
	s_nop 0
	global_load_lds_dwordx4 v130, s[28:29]
	s_waitcnt vmcnt(8)
	s_waitcnt lgkmcnt(0)
	s_barrier
	s_setprio 1
	v_mfma_f32_16x16x32_bf16 v[124:127], v[138:141], v[176:179], v[124:127]
	v_mfma_f32_16x16x32_bf16 v[120:123], v[152:155], v[176:179], v[120:123]
	v_mfma_f32_16x16x32_bf16 v[108:111], v[138:141], v[184:187], v[108:111]
	v_mfma_f32_16x16x32_bf16 v[104:107], v[152:155], v[184:187], v[104:107]
	v_mfma_f32_16x16x32_bf16 v[92:95], v[138:141], v[192:195], v[92:95]
	v_mfma_f32_16x16x32_bf16 v[88:91], v[152:155], v[192:195], v[88:91]
	v_mfma_f32_16x16x32_bf16 v[76:79], v[138:141], v[200:203], v[76:79]
	v_mfma_f32_16x16x32_bf16 v[72:75], v[152:155], v[200:203], v[72:75]
	v_mfma_f32_16x16x32_bf16 v[124:127], v[148:151], v[180:183], v[124:127]
	v_mfma_f32_16x16x32_bf16 v[120:123], v[156:159], v[180:183], v[120:123]
	v_mfma_f32_16x16x32_bf16 v[108:111], v[148:151], v[188:191], v[108:111]
	v_mfma_f32_16x16x32_bf16 v[104:107], v[156:159], v[188:191], v[104:107]
	v_mfma_f32_16x16x32_bf16 v[92:95], v[148:151], v[196:199], v[92:95]
	v_mfma_f32_16x16x32_bf16 v[88:91], v[156:159], v[196:199], v[88:91]
	v_mfma_f32_16x16x32_bf16 v[76:79], v[148:151], v[204:207], v[76:79]
	v_mfma_f32_16x16x32_bf16 v[72:75], v[156:159], v[204:207], v[72:75]
	v_mfma_f32_16x16x32_bf16 v[116:119], v[160:163], v[176:179], v[116:119]
	v_mfma_f32_16x16x32_bf16 v[112:115], v[168:171], v[176:179], v[112:115]
	v_mfma_f32_16x16x32_bf16 v[100:103], v[160:163], v[184:187], v[100:103]
	v_mfma_f32_16x16x32_bf16 v[96:99], v[168:171], v[184:187], v[96:99]
	v_mfma_f32_16x16x32_bf16 v[84:87], v[160:163], v[192:195], v[84:87]
	v_mfma_f32_16x16x32_bf16 v[80:83], v[168:171], v[192:195], v[80:83]
	v_mfma_f32_16x16x32_bf16 v[68:71], v[160:163], v[200:203], v[68:71]
	v_mfma_f32_16x16x32_bf16 v[64:67], v[168:171], v[200:203], v[64:67]
	v_mfma_f32_16x16x32_bf16 v[116:119], v[164:167], v[180:183], v[116:119]
	v_mfma_f32_16x16x32_bf16 v[112:115], v[172:175], v[180:183], v[112:115]
	v_mfma_f32_16x16x32_bf16 v[100:103], v[164:167], v[188:191], v[100:103]
	v_mfma_f32_16x16x32_bf16 v[96:99], v[172:175], v[188:191], v[96:99]
	v_mfma_f32_16x16x32_bf16 v[84:87], v[164:167], v[196:199], v[84:87]
	v_mfma_f32_16x16x32_bf16 v[80:83], v[172:175], v[196:199], v[80:83]
	v_mfma_f32_16x16x32_bf16 v[68:71], v[164:167], v[204:207], v[68:71]
	v_mfma_f32_16x16x32_bf16 v[64:67], v[172:175], v[204:207], v[64:67]
	s_setprio 0
	s_barrier
	s_add_i32 s10, s10, s31
	v_lshl_add_u64 v[142:143], v[142:143], 0, s[94:95]
	s_mov_b32 m0, s10
	ds_read_b128 v[176:179], v147 offset:49152
	ds_read_b128 v[180:183], v147 offset:50176
	ds_read_b128 v[184:187], v147 offset:51200
	ds_read_b128 v[188:191], v147 offset:52224
	ds_read_b128 v[192:195], v147 offset:53248
	ds_read_b128 v[196:199], v147 offset:54272
	ds_read_b128 v[200:203], v147 offset:55296
	ds_read_b128 v[204:207], v147 offset:56320
	global_load_lds_dwordx4 v[142:143], off
	s_add_i32 m0, s10, 0x2000
	s_add_u32 s26, s26, 0x100080
	v_lshl_add_u64 v[142:143], v[222:223], 0, s[94:95]
	s_addc_u32 s27, s27, 0
	s_add_i32 s10, s11, s31
	global_load_lds_dwordx4 v[142:143], off
	s_mov_b32 m0, s10
	s_nop 0
	global_load_lds_dwordx4 v208, s[26:27]
	v_lshl_add_u64 v[142:143], s[26:27], 0, v[128:129]
	s_add_i32 m0, s10, 0x2000
	s_nop 0
	global_load_lds_dwordx4 v[142:143], off
	v_lshl_add_u64 v[142:143], v[224:225], 0, s[94:95]
	s_mov_b32 m0, s40
	s_nop 0
	global_load_lds_dwordx4 v[142:143], off
	v_lshl_add_u64 v[142:143], v[236:237], 0, s[94:95]
	s_mov_b32 m0, s41
	s_nop 0
	global_load_lds_dwordx4 v[142:143], off
	s_waitcnt vmcnt(8)
	s_waitcnt lgkmcnt(0)
	s_barrier
	s_setprio 1
	v_mfma_f32_16x16x32_bf16 v[60:63], v[138:141], v[176:179], v[60:63]
	v_mfma_f32_16x16x32_bf16 v[56:59], v[152:155], v[176:179], v[56:59]
	v_mfma_f32_16x16x32_bf16 v[44:47], v[138:141], v[184:187], v[44:47]
	v_mfma_f32_16x16x32_bf16 v[40:43], v[152:155], v[184:187], v[40:43]
	v_mfma_f32_16x16x32_bf16 v[28:31], v[138:141], v[192:195], v[28:31]
	v_mfma_f32_16x16x32_bf16 v[24:27], v[152:155], v[192:195], v[24:27]
	v_mfma_f32_16x16x32_bf16 v[12:15], v[138:141], v[200:203], v[12:15]
	v_mfma_f32_16x16x32_bf16 v[8:11], v[152:155], v[200:203], v[8:11]
	v_mfma_f32_16x16x32_bf16 v[60:63], v[148:151], v[180:183], v[60:63]
	v_mfma_f32_16x16x32_bf16 v[56:59], v[156:159], v[180:183], v[56:59]
	v_mfma_f32_16x16x32_bf16 v[44:47], v[148:151], v[188:191], v[44:47]
	v_mfma_f32_16x16x32_bf16 v[40:43], v[156:159], v[188:191], v[40:43]
	v_mfma_f32_16x16x32_bf16 v[28:31], v[148:151], v[196:199], v[28:31]
	v_mfma_f32_16x16x32_bf16 v[24:27], v[156:159], v[196:199], v[24:27]
	v_mfma_f32_16x16x32_bf16 v[12:15], v[148:151], v[204:207], v[12:15]
	v_mfma_f32_16x16x32_bf16 v[8:11], v[156:159], v[204:207], v[8:11]
	v_mfma_f32_16x16x32_bf16 v[52:55], v[160:163], v[176:179], v[52:55]
	v_mfma_f32_16x16x32_bf16 v[48:51], v[168:171], v[176:179], v[48:51]
	v_mfma_f32_16x16x32_bf16 v[36:39], v[160:163], v[184:187], v[36:39]
	v_mfma_f32_16x16x32_bf16 v[32:35], v[168:171], v[184:187], v[32:35]
	v_mfma_f32_16x16x32_bf16 v[20:23], v[160:163], v[192:195], v[20:23]
	v_mfma_f32_16x16x32_bf16 v[16:19], v[168:171], v[192:195], v[16:19]
	v_mfma_f32_16x16x32_bf16 v[4:7], v[160:163], v[200:203], v[4:7]
	v_mfma_f32_16x16x32_bf16 v[0:3], v[168:171], v[200:203], v[0:3]
	v_mfma_f32_16x16x32_bf16 v[52:55], v[164:167], v[180:183], v[52:55]
	v_mfma_f32_16x16x32_bf16 v[48:51], v[172:175], v[180:183], v[48:51]
	v_mfma_f32_16x16x32_bf16 v[36:39], v[164:167], v[188:191], v[36:39]
	v_mfma_f32_16x16x32_bf16 v[32:35], v[172:175], v[188:191], v[32:35]
	v_mfma_f32_16x16x32_bf16 v[20:23], v[164:167], v[196:199], v[20:23]
	v_mfma_f32_16x16x32_bf16 v[16:19], v[172:175], v[196:199], v[16:19]
	v_mfma_f32_16x16x32_bf16 v[4:7], v[164:167], v[204:207], v[4:7]
	v_mfma_f32_16x16x32_bf16 v[0:3], v[172:175], v[204:207], v[0:3]
	s_setprio 0
	s_barrier
	s_add_i32 s82, s82, 2
	s_add_u32 s24, s24, 0x100
	s_addc_u32 s25, s25, 0
	s_add_u32 s77, s77, 0x100
	s_addc_u32 s80, s80, 0
	s_cmp_gt_u32 s82, 61
	s_cbranch_scc0 .LBB0_869
	v_lshl_add_u32 v140, s70, 8, v144
	v_lshl_or_b32 v138, s43, 8, v146
	v_lshlrev_b32_e32 v139, 2, v140
	v_lshlrev_b32_e32 v140, 11, v140
	v_lshl_add_u32 v138, v138, 1, v140
	s_mov_b64 s[100:101], s[46:47]
	global_load_dwordx4 v[148:151], v138, s[100:101]
	global_load_dwordx4 v[152:155], v138, s[100:101] offset:256
	s_add_u32 s100, s100, 0x8000
	s_addc_u32 s101, s101, 0
	global_load_dwordx4 v[156:159], v138, s[100:101]
	global_load_dwordx4 v[160:163], v138, s[100:101] offset:256
	s_add_u32 s100, s100, 0x8000
	s_addc_u32 s101, s101, 0
	global_load_dwordx4 v[164:167], v138, s[100:101]
	global_load_dwordx4 v[168:171], v138, s[100:101] offset:256
	s_add_u32 s100, s100, 0x8000
	s_addc_u32 s101, s101, 0
	global_load_dwordx4 v[172:175], v138, s[100:101]
	global_load_dwordx4 v[176:179], v138, s[100:101] offset:256
	s_add_u32 s100, s100, 0x28000
	s_addc_u32 s101, s101, 0
	global_load_dwordx4 v[180:183], v138, s[100:101]
	global_load_dwordx4 v[184:187], v138, s[100:101] offset:256
	s_add_u32 s100, s100, 0x8000
	s_addc_u32 s101, s101, 0
	global_load_dwordx4 v[188:191], v138, s[100:101]
	global_load_dwordx4 v[192:195], v138, s[100:101] offset:256
	s_add_u32 s100, s100, 0x8000
	s_addc_u32 s101, s101, 0
	global_load_dwordx4 v[196:199], v138, s[100:101]
	global_load_dwordx4 v[200:203], v138, s[100:101] offset:256
	s_add_u32 s100, s100, 0x8000
	s_addc_u32 s101, s101, 0
	global_load_dwordx4 v[204:207], v138, s[100:101]
	global_load_dwordx4 v[236:239], v138, s[100:101] offset:256
	s_and_b64 vcc, exec, s[14:15]
	s_cbranch_vccz .LBB0_872
	s_barrier
